# static setprio 1 on waves 0-3 (component-0 half) instead of waves 4-7
# speedup vs baseline: 1.0103x; 1.0020x over previous
; #define LAS __attribute__((address_space(3)))
; __device__ __forceinline__ int opaque_tid() { int t = threadIdx.x; asm volatile("" : "+v"(t)); return t; }
; __device__ __forceinline__ int v_st_nat(int k, int c) { return ((k >> 3) * 2 + (c >> 5)) * 512 + ((k & 7) * 32 + (c & 31)) * 2; }
; __device__ __forceinline__ int v_rd_base(int lane) { return ((lane & 3) << 3) | (((lane >> 2) & 3) << 6) | (((lane >> 4) & 1) << 5) | (((lane >> 5) & 1) << 8); }
; #define AT_LOAD(K0, K1, V0, V1, T) do { const size_t e_ = (size_t)(128 * (T) + sr) * 64 + sc; \
;         K0 = *(const bf16x8*)(kcp + e_); V0 = *(const bf16x8*)(vcp + e_); K1 = *(const bf16x8*)(kcp + e_ + 64 * 64); V1 = *(const bf16x8*)(vcp + e_ + 64 * 64); } while (0)
; #define AT_STORE(K0, K1, V0, V1, BUF) do { *(LAS bf16x8*)(lds + AT_K + (BUF) * AT_KB + kst0) = K0; *(LAS bf16x8*)(lds + AT_K + (BUF) * AT_KB + kst1) = K1; \
;         *(LAS bf16x8*)(lds + AT_V + (BUF) * AT_VB + vst0) = V0; *(LAS bf16x8*)(lds + AT_V + (BUF) * AT_VB + vst1) = V1; } while (0)
; template <int VAR>
; __device__ __forceinline__ void attn_unit(const Args& a, int l, int b, int h, int qrow0  , bool ctxu, const bf16* Z, bf16* Y, LAS unsigned char* lds) {
;     const int tid = opaque_tid(), lane = tid & 63, wave = __builtin_amdgcn_readfirstlane(tid >> 6), r32 = lane & 31, hi = lane >> 5;
;     const int comp = wave >> 2, wq = wave & 3;
;     const int NT = ctxu ? 2 : 66;
;     const bf16* kcp = (const bf16*)(a.ws + WS_KC) + (size_t)(b * 4 + h) * 8448 * 64; const bf16* vcp = (const bf16*)(a.ws + WS_VC) + (size_t)(b * 4 + h) * 8448 * 64;
;     bf16x8 q0, q1;
;     { const bf16* qp = Z + (size_t)(qrow0 + wq * 32 + r32) * DIN + 512 + h * 64 + comp * 32 + hi * 8; q0 = *(const bf16x8*)(qp); q1 = *(const bf16x8*)(qp + 16); }
;     const int sr = tid >> 3, sc = (tid & 7) * 8;
;     const int kst0 = sr * 144 + sc * 2, kst1 = kst0 + 64 * 144, vst0 = v_st_nat(sr, sc), vst1 = v_st_nat(sr + 64, sc);
;     const int vb0 = (int)(unsigned)(uintptr_t)(lds + AT_V) + v_rd_base(lane);
;     LAS float* wsf = (LAS float*)(lds + AT_WS) + wave * 64;
;     f32x16 negm = f32x16{}, o0 = f32x16{}, o1 = f32x16{}, lacc = f32x16{};
;     float m = 0.f;
;     bf16x8 ka0, ka1, va0, va1, kb0, kb1, vb0_, vb1_;
;     ...
;     AT_LOAD(ka0, ka1, va0, va1, 0); AT_LOAD(kb0, kb1, vb0_, vb1_, 1); AT_STORE(ka0, ka1, va0, va1, 0);
.LBB0_431:
	v_mov_b32_e32 v79, 0
	v_readfirstlane_b32 s36, v230
	v_readfirstlane_b32 s37, v231
	s_mov_b32 s94, 1
	s_mov_b32 s95, 1
	s_mov_b32 s33, 0
	s_lshr_b32 s50, s29, 6
	s_lshl_b32 s51, s50, 10
	s_lshl_b32 s93, s50, 8
	s_lshl_b32 s50, s50, 3
	v_lshrrev_b32_e32 v132, 3, v227
	v_add_u32_e32 v132, s50, v132
	v_bfe_u32 v133, v132, 1, 3
	v_and_b32_e32 v134, 7, v227
	v_xor_b32_e32 v134, v134, v133
	v_lshlrev_b32_e32 v132, 7, v132
	v_lshl_or_b32 v158, v134, 4, v132
	v_add_u32_e32 v159, 0x2000, v158
	v_bfe_u32 v132, v227, 2, 3
	v_add_u32_e32 v132, s50, v132
	v_lshrrev_b32_e32 v133, 5, v227
	v_and_b32_e32 v134, 3, v227
	v_lshlrev_b32_e32 v133, 6, v133
	v_lshl_or_b32 v133, v134, 4, v133
	v_lshl_or_b32 v160, v132, 7, v133
	v_add_u32_e32 v161, 0x2000, v160
	s_lshl_b32 s50, s8, 2
	v_add_u32_e32 v132, s50, v248
	v_bfe_u32 v133, v247, 1, 3
	v_xor_b32_e32 v132, v132, v133
	v_lshlrev_b32_e32 v133, 7, v247
	v_lshl_or_b32 v144, v132, 4, v133
	v_xor_b32_e32 v145, 32, v144
	v_add_u32_e32 v146, 0x3000, v249
	s_add_u32 s93, s93, 0x19800
	v_lshlrev_b32_e32 v132, 2, v247
	v_add_u32_e32 v148, s93, v132
	v_lshlrev_b32_e32 v132, 4, v248
	v_add_u32_e32 v147, s93, v132
	v_mov_b32_e32 v80, 0
	v_mov_b32_e32 v200, 0
	v_mov_b32_e32 v81, 0
	v_mov_b32_e32 v201, 0
	v_mov_b32_e32 v82, 0
	v_mov_b32_e32 v202, 0
	v_mov_b32_e32 v83, 0
	v_mov_b32_e32 v203, 0
	v_mov_b32_e32 v84, 0
	v_mov_b32_e32 v204, 0
	v_mov_b32_e32 v85, 0
	v_mov_b32_e32 v205, 0
	v_mov_b32_e32 v86, 0
	v_mov_b32_e32 v206, 0
	v_mov_b32_e32 v87, 0
	v_mov_b32_e32 v207, 0
	v_mov_b32_e32 v88, 0
	v_mov_b32_e32 v208, 0
	v_mov_b32_e32 v89, 0
	v_mov_b32_e32 v209, 0
	v_mov_b32_e32 v90, 0
	v_mov_b32_e32 v210, 0
	v_mov_b32_e32 v91, 0
	v_mov_b32_e32 v211, 0
	v_mov_b32_e32 v92, 0
	v_mov_b32_e32 v212, 0
	v_mov_b32_e32 v93, 0
	v_mov_b32_e32 v213, 0
	v_mov_b32_e32 v94, 0
	v_mov_b32_e32 v214, 0
	v_mov_b32_e32 v95, 0
	v_mov_b32_e32 v215, 0
	v_mov_b32_e32 v128, 0
	v_mov_b32_e32 v129, 0
	v_mov_b32_e32 v130, 0
	v_mov_b32_e32 v131, 0
	v_mov_b32_e32 v149, 0
	s_sub_u32 s36, s36, s51
	s_subb_u32 s37, s37, 0
	s_add_u32 s48, s36, 0x1d200000
	s_addc_u32 s49, s37, 0
	s_add_u32 s36, s36, 0x1c000000
	s_addc_u32 s37, s37, 0
	s_cmp_eq_u32 s8, 0
	s_cbranch_scc0 .Lat_noprio
	s_setprio 1
